# epilogue rstd: removed never-taken denormal rescue around v_rsq; SwiGLU epilogue re-associated as (g*u)*(r^2*sigmoid(g*r)) with two gate pairs interleaved (fewer VALU ops, no hazard nops)
# speedup vs baseline: 1.0150x; 1.0029x over previous
.LBB0_380:
	s_lshl_b32 s5, s5, 8
	s_lshl_b32 s6, s6, 7
	s_add_i32 s5, s5, s6
	v_add_u32_e32 v130, s5, v222
	v_ashrrev_i32_e32 v131, 31, v130
	v_lshlrev_b64 v[132:133], 6, v[130:131]
	v_lshl_add_u64 v[132:133], v[204:205], 0, v[132:133]
	global_load_dwordx4 v[136:139], v[132:133], off
	global_load_dwordx4 v[140:143], v[132:133], off offset:1024
	global_load_dwordx4 v[144:147], v[132:133], off offset:2048
	global_load_dwordx4 v[148:151], v[132:133], off offset:3072
	v_add_u32_e32 v168, 0x80, v130
	v_ashrrev_i32_e32 v169, 31, v168
	v_lshlrev_b64 v[168:169], 6, v[168:169]
	v_lshl_add_u64 v[168:169], v[204:205], 0, v[168:169]
	global_load_dwordx4 v[152:155], v[168:169], off
	global_load_dwordx4 v[156:159], v[168:169], off offset:1024
	global_load_dwordx4 v[160:163], v[168:169], off offset:2048
	global_load_dwordx4 v[164:167], v[168:169], off offset:3072
	s_lshl_b32 s4, s4, 7
	s_ashr_i32 s5, s4, 31
	s_lshl_b64 s[38:39], s[4:5], 1
	s_waitcnt vmcnt(7)
	v_add_f32_e32 v131, v136, v137
	v_add_f32_e32 v132, v138, v139
	v_add_f32_e32 v131, v131, v132
	v_mov_b32_e32 v132, v131
	s_nop 1
	v_permlane16_swap_b32_e32 v131, v132
	v_add_f32_e32 v131, v131, v132
	v_mov_b32_e32 v132, v131
	s_nop 1
	v_permlane32_swap_b32_e32 v131, v132
	v_add_f32_e32 v131, v131, v132
	v_fmamk_f32 v131, v131, 0x3a800000, v225
	v_rsq_f32_e32 v132, v131
	s_nop 0
	v_mul_f32_e32 v133, v132, v132
	v_mul_f32_e32 v132, 0xbfb8aa3b, v132
	v_pk_mul_f32 v[134:135], v[126:127], v[132:133] op_sel_hi:[1,0]
	v_pk_mul_f32 v[126:127], v[126:127], v[122:123]
	v_pk_mul_f32 v[122:123], v[128:129], v[132:133] op_sel_hi:[1,0]
	v_pk_mul_f32 v[128:129], v[128:129], v[124:125]
	v_exp_f32_e32 v134, v134
	v_exp_f32_e32 v135, v135
	v_exp_f32_e32 v122, v122
	v_exp_f32_e32 v123, v123
	v_pk_add_f32 v[134:135], v[134:135], 1.0 op_sel_hi:[1,0]
	v_pk_add_f32 v[122:123], v[122:123], 1.0 op_sel_hi:[1,0]
	v_rcp_f32_e32 v134, v134
	v_rcp_f32_e32 v135, v135
	v_rcp_f32_e32 v122, v122
	v_rcp_f32_e32 v123, v123
	v_pk_mul_f32 v[134:135], v[134:135], v[132:133] op_sel:[0,1]
	v_pk_mul_f32 v[122:123], v[122:123], v[132:133] op_sel:[0,1]
	s_nop 0
	v_pk_mul_f32 v[124:125], v[128:129], v[122:123]
	v_pk_mul_f32 v[122:123], v[126:127], v[134:135]
	v_pk_mul_f32 v[134:135], v[118:119], v[132:133] op_sel_hi:[1,0]
	v_pk_mul_f32 v[118:119], v[118:119], v[114:115]
	v_pk_mul_f32 v[126:127], v[120:121], v[132:133] op_sel_hi:[1,0]
	v_pk_mul_f32 v[120:121], v[120:121], v[116:117]
	v_exp_f32_e32 v134, v134
	v_exp_f32_e32 v135, v135
	v_exp_f32_e32 v126, v126
	v_exp_f32_e32 v127, v127
	v_pk_add_f32 v[134:135], v[134:135], 1.0 op_sel_hi:[1,0]
	v_pk_add_f32 v[126:127], v[126:127], 1.0 op_sel_hi:[1,0]
	v_rcp_f32_e32 v134, v134
	v_rcp_f32_e32 v135, v135
	v_rcp_f32_e32 v126, v126
	v_rcp_f32_e32 v127, v127
	v_pk_mul_f32 v[134:135], v[134:135], v[132:133] op_sel:[0,1]
	v_pk_mul_f32 v[126:127], v[126:127], v[132:133] op_sel:[0,1]
	v_pk_mul_f32 v[118:119], v[118:119], v[134:135]
	v_pk_mul_f32 v[120:121], v[120:121], v[126:127]
	v_cvt_pk_bf16_f32 v116, v118, v119
	v_mov_b64_e32 v[118:119], s[62:63]
	v_cvt_pk_bf16_f32 v117, v120, v121
	v_mad_i64_i32 v[120:121], s[6:7], v130, s16, v[118:119]
	v_lshl_add_u64 v[120:121], v[120:121], 0, s[38:39]
	v_lshl_add_u64 v[120:121], v[120:121], 0, s[68:69]
	v_cvt_pk_bf16_f32 v114, v122, v123
	v_cvt_pk_bf16_f32 v115, v124, v125
	v_lshl_add_u64 v[120:121], v[120:121], 0, v[96:97]
	global_store_dwordx4 v[120:121], v[114:117], off sc1
	s_nop 1
	v_or_b32_e32 v114, 16, v130
	v_ashrrev_i32_e32 v115, 31, v114
	v_lshlrev_b64 v[116:117], 6, v[114:115]
	v_lshl_add_u64 v[116:117], v[204:205], 0, v[116:117]
	s_waitcnt vmcnt(7)
	v_add_f32_e32 v115, v140, v141
	v_add_f32_e32 v116, v142, v143
	v_add_f32_e32 v115, v115, v116
	v_mov_b32_e32 v116, v115
	s_nop 1
	v_permlane16_swap_b32_e32 v115, v116
	v_add_f32_e32 v115, v115, v116
	v_mov_b32_e32 v116, v115
	s_nop 1
	v_permlane32_swap_b32_e32 v115, v116
	v_add_f32_e32 v115, v115, v116
	v_fmamk_f32 v115, v115, 0x3a800000, v225
	v_rsq_f32_e32 v116, v115
	s_nop 0
	v_mul_f32_e32 v117, v116, v116
	v_mul_f32_e32 v116, 0xbfb8aa3b, v116
	v_pk_mul_f32 v[120:121], v[110:111], v[116:117] op_sel_hi:[1,0]
	v_pk_mul_f32 v[110:111], v[110:111], v[106:107]
	v_pk_mul_f32 v[106:107], v[112:113], v[116:117] op_sel_hi:[1,0]
	v_pk_mul_f32 v[112:113], v[112:113], v[108:109]
	v_exp_f32_e32 v120, v120
	v_exp_f32_e32 v121, v121
	v_exp_f32_e32 v106, v106
	v_exp_f32_e32 v107, v107
	v_pk_add_f32 v[120:121], v[120:121], 1.0 op_sel_hi:[1,0]
	v_pk_add_f32 v[106:107], v[106:107], 1.0 op_sel_hi:[1,0]
	v_rcp_f32_e32 v120, v120
	v_rcp_f32_e32 v121, v121
	v_rcp_f32_e32 v106, v106
	v_rcp_f32_e32 v107, v107
	v_pk_mul_f32 v[120:121], v[120:121], v[116:117] op_sel:[0,1]
	v_pk_mul_f32 v[106:107], v[106:107], v[116:117] op_sel:[0,1]
	s_nop 0
	v_pk_mul_f32 v[108:109], v[112:113], v[106:107]
	v_pk_mul_f32 v[106:107], v[110:111], v[120:121]
	v_pk_mul_f32 v[120:121], v[102:103], v[116:117] op_sel_hi:[1,0]
	v_pk_mul_f32 v[102:103], v[102:103], v[98:99]
	v_pk_mul_f32 v[110:111], v[104:105], v[116:117] op_sel_hi:[1,0]
	v_pk_mul_f32 v[104:105], v[104:105], v[100:101]
	v_exp_f32_e32 v120, v120
	v_exp_f32_e32 v121, v121
	v_exp_f32_e32 v110, v110
	v_exp_f32_e32 v111, v111
	v_pk_add_f32 v[120:121], v[120:121], 1.0 op_sel_hi:[1,0]
	v_pk_add_f32 v[110:111], v[110:111], 1.0 op_sel_hi:[1,0]
	v_rcp_f32_e32 v120, v120
	v_rcp_f32_e32 v121, v121
	v_rcp_f32_e32 v110, v110
	v_rcp_f32_e32 v111, v111
	v_pk_mul_f32 v[120:121], v[120:121], v[116:117] op_sel:[0,1]
	v_pk_mul_f32 v[110:111], v[110:111], v[116:117] op_sel:[0,1]
	v_pk_mul_f32 v[102:103], v[102:103], v[120:121]
	v_pk_mul_f32 v[104:105], v[104:105], v[110:111]
	v_cvt_pk_bf16_f32 v100, v102, v103
	v_mad_i64_i32 v[102:103], s[4:5], v114, s16, v[118:119]
	v_lshl_add_u64 v[102:103], v[102:103], 0, s[38:39]
	v_lshl_add_u64 v[102:103], v[102:103], 0, s[68:69]
	v_cvt_pk_bf16_f32 v98, v106, v107
	v_cvt_pk_bf16_f32 v99, v108, v109
	v_cvt_pk_bf16_f32 v101, v104, v105
	v_lshl_add_u64 v[102:103], v[102:103], 0, v[96:97]
	global_store_dwordx4 v[102:103], v[98:101], off sc1
	s_nop 1
	v_or_b32_e32 v98, 32, v130
	v_ashrrev_i32_e32 v99, 31, v98
	v_lshlrev_b64 v[100:101], 6, v[98:99]
	v_lshl_add_u64 v[100:101], v[204:205], 0, v[100:101]
	s_waitcnt vmcnt(7)
	v_add_f32_e32 v99, v144, v145
	v_add_f32_e32 v100, v146, v147
	v_add_f32_e32 v99, v99, v100
	v_mov_b32_e32 v100, v99
	s_nop 1
	v_permlane16_swap_b32_e32 v99, v100
	v_add_f32_e32 v99, v99, v100
	v_mov_b32_e32 v100, v99
	s_nop 1
	v_permlane32_swap_b32_e32 v99, v100
	v_add_f32_e32 v99, v99, v100
	v_fmamk_f32 v99, v99, 0x3a800000, v225
	v_rsq_f32_e32 v100, v99
	s_nop 0
	v_mul_f32_e32 v101, v100, v100
	v_mul_f32_e32 v100, 0xbfb8aa3b, v100
	v_pk_mul_f32 v[102:103], v[92:93], v[100:101] op_sel_hi:[1,0]
	v_pk_mul_f32 v[92:93], v[92:93], v[88:89]
	v_pk_mul_f32 v[88:89], v[94:95], v[100:101] op_sel_hi:[1,0]
	v_pk_mul_f32 v[94:95], v[94:95], v[90:91]
	v_exp_f32_e32 v102, v102
	v_exp_f32_e32 v103, v103
	v_exp_f32_e32 v88, v88
	v_exp_f32_e32 v89, v89
	v_pk_add_f32 v[102:103], v[102:103], 1.0 op_sel_hi:[1,0]
	v_pk_add_f32 v[88:89], v[88:89], 1.0 op_sel_hi:[1,0]
	v_rcp_f32_e32 v102, v102
	v_rcp_f32_e32 v103, v103
	v_rcp_f32_e32 v88, v88
	v_rcp_f32_e32 v89, v89
	v_pk_mul_f32 v[102:103], v[102:103], v[100:101] op_sel:[0,1]
	v_pk_mul_f32 v[88:89], v[88:89], v[100:101] op_sel:[0,1]
	s_nop 0
	v_pk_mul_f32 v[90:91], v[94:95], v[88:89]
	v_pk_mul_f32 v[88:89], v[92:93], v[102:103]
	v_pk_mul_f32 v[102:103], v[84:85], v[100:101] op_sel_hi:[1,0]
	v_pk_mul_f32 v[84:85], v[84:85], v[80:81]
	v_pk_mul_f32 v[92:93], v[86:87], v[100:101] op_sel_hi:[1,0]
	v_pk_mul_f32 v[86:87], v[86:87], v[82:83]
	v_exp_f32_e32 v102, v102
	v_exp_f32_e32 v103, v103
	v_exp_f32_e32 v92, v92
	v_exp_f32_e32 v93, v93
	v_pk_add_f32 v[102:103], v[102:103], 1.0 op_sel_hi:[1,0]
	v_pk_add_f32 v[92:93], v[92:93], 1.0 op_sel_hi:[1,0]
	v_rcp_f32_e32 v102, v102
	v_rcp_f32_e32 v103, v103
	v_rcp_f32_e32 v92, v92
	v_rcp_f32_e32 v93, v93
	v_pk_mul_f32 v[102:103], v[102:103], v[100:101] op_sel:[0,1]
	v_pk_mul_f32 v[92:93], v[92:93], v[100:101] op_sel:[0,1]
	v_pk_mul_f32 v[84:85], v[84:85], v[102:103]
	v_pk_mul_f32 v[86:87], v[86:87], v[92:93]
	v_cvt_pk_bf16_f32 v82, v84, v85
	v_mad_i64_i32 v[84:85], s[4:5], v98, s16, v[118:119]
	v_lshl_add_u64 v[84:85], v[84:85], 0, s[38:39]
	v_lshl_add_u64 v[84:85], v[84:85], 0, s[68:69]
	v_cvt_pk_bf16_f32 v80, v88, v89
	v_cvt_pk_bf16_f32 v81, v90, v91
	v_cvt_pk_bf16_f32 v83, v86, v87
	v_lshl_add_u64 v[84:85], v[84:85], 0, v[96:97]
	global_store_dwordx4 v[84:85], v[80:83], off sc1
	s_nop 1
	v_or_b32_e32 v80, 48, v130
	v_ashrrev_i32_e32 v81, 31, v80
	v_lshlrev_b64 v[82:83], 6, v[80:81]
	v_lshl_add_u64 v[82:83], v[204:205], 0, v[82:83]
	s_waitcnt vmcnt(7)
	v_add_f32_e32 v81, v148, v149
	v_add_f32_e32 v82, v150, v151
	v_add_f32_e32 v81, v81, v82
	v_mov_b32_e32 v82, v81
	s_nop 1
	v_permlane16_swap_b32_e32 v81, v82
	v_add_f32_e32 v81, v81, v82
	v_mov_b32_e32 v82, v81
	s_nop 1
	v_permlane32_swap_b32_e32 v81, v82
	v_add_f32_e32 v81, v81, v82
	v_fmamk_f32 v81, v81, 0x3a800000, v225
	v_rsq_f32_e32 v82, v81
	s_nop 0
	v_mul_f32_e32 v83, v82, v82
	v_mul_f32_e32 v82, 0xbfb8aa3b, v82
	v_pk_mul_f32 v[84:85], v[76:77], v[82:83] op_sel_hi:[1,0]
	v_pk_mul_f32 v[76:77], v[76:77], v[72:73]
	v_pk_mul_f32 v[72:73], v[78:79], v[82:83] op_sel_hi:[1,0]
	v_pk_mul_f32 v[78:79], v[78:79], v[74:75]
	v_exp_f32_e32 v84, v84
	v_exp_f32_e32 v85, v85
	v_exp_f32_e32 v72, v72
	v_exp_f32_e32 v73, v73
	v_pk_add_f32 v[84:85], v[84:85], 1.0 op_sel_hi:[1,0]
	v_pk_add_f32 v[72:73], v[72:73], 1.0 op_sel_hi:[1,0]
	v_rcp_f32_e32 v84, v84
	v_rcp_f32_e32 v85, v85
	v_rcp_f32_e32 v72, v72
	v_rcp_f32_e32 v73, v73
	v_pk_mul_f32 v[84:85], v[84:85], v[82:83] op_sel:[0,1]
	v_pk_mul_f32 v[72:73], v[72:73], v[82:83] op_sel:[0,1]
	s_nop 0
	v_pk_mul_f32 v[74:75], v[78:79], v[72:73]
	v_pk_mul_f32 v[72:73], v[76:77], v[84:85]
	v_pk_mul_f32 v[84:85], v[68:69], v[82:83] op_sel_hi:[1,0]
	v_pk_mul_f32 v[68:69], v[68:69], v[64:65]
	v_pk_mul_f32 v[76:77], v[70:71], v[82:83] op_sel_hi:[1,0]
	v_pk_mul_f32 v[70:71], v[70:71], v[66:67]
	v_exp_f32_e32 v84, v84
	v_exp_f32_e32 v85, v85
	v_exp_f32_e32 v76, v76
	v_exp_f32_e32 v77, v77
	v_pk_add_f32 v[84:85], v[84:85], 1.0 op_sel_hi:[1,0]
	v_pk_add_f32 v[76:77], v[76:77], 1.0 op_sel_hi:[1,0]
	v_rcp_f32_e32 v84, v84
	v_rcp_f32_e32 v85, v85
	v_rcp_f32_e32 v76, v76
	v_rcp_f32_e32 v77, v77
	v_pk_mul_f32 v[84:85], v[84:85], v[82:83] op_sel:[0,1]
	v_pk_mul_f32 v[76:77], v[76:77], v[82:83] op_sel:[0,1]
	v_pk_mul_f32 v[68:69], v[68:69], v[84:85]
	v_pk_mul_f32 v[70:71], v[70:71], v[76:77]
	v_cmp_ne_u32_e32 vcc, 0, v247
	s_and_b64 vcc, exec, vcc
	v_cvt_pk_bf16_f32 v66, v68, v69
	v_mad_i64_i32 v[68:69], s[4:5], v80, s16, v[118:119]
	v_lshl_add_u64 v[68:69], v[68:69], 0, s[38:39]
	v_lshl_add_u64 v[68:69], v[68:69], 0, s[68:69]
	v_cvt_pk_bf16_f32 v64, v72, v73
	v_cvt_pk_bf16_f32 v65, v74, v75
	v_cvt_pk_bf16_f32 v67, v70, v71
	v_lshl_add_u64 v[68:69], v[68:69], 0, v[96:97]
	global_store_dwordx4 v[68:69], v[64:67], off sc1
	s_cbranch_vccz .LBB0_382
	s_waitcnt vmcnt(4)
	s_and_b64 vcc, exec, s[36:37]
	s_mov_b64 s[30:31], -1
	s_cbranch_vccnz .LBB0_349
	s_branch .LBB0_383
.LBB0_382:
	s_nop 0
	v_add_u32_e32 v64, 0x80, v130
	v_ashrrev_i32_e32 v65, 31, v64
	v_lshlrev_b64 v[66:67], 6, v[64:65]
	v_lshl_add_u64 v[66:67], v[204:205], 0, v[66:67]
	s_waitcnt vmcnt(7)
	v_add_f32_e32 v65, v152, v153
	v_add_f32_e32 v66, v154, v155
	v_add_f32_e32 v65, v65, v66
	v_mov_b32_e32 v66, v65
	s_nop 1
	v_permlane16_swap_b32_e32 v65, v66
	v_add_f32_e32 v65, v65, v66
	v_mov_b32_e32 v66, v65
	s_nop 1
	v_permlane32_swap_b32_e32 v65, v66
	v_add_f32_e32 v65, v65, v66
	v_fmamk_f32 v65, v65, 0x3a800000, v225
	v_rsq_f32_e32 v66, v65
	s_nop 0
	v_mul_f32_e32 v67, v66, v66
	v_mul_f32_e32 v66, 0xbfb8aa3b, v66
	v_pk_mul_f32 v[68:69], v[48:49], v[66:67] op_sel_hi:[1,0]
	v_pk_mul_f32 v[48:49], v[48:49], v[60:61]
	v_pk_mul_f32 v[60:61], v[50:51], v[66:67] op_sel_hi:[1,0]
	v_pk_mul_f32 v[50:51], v[50:51], v[62:63]
	v_exp_f32_e32 v68, v68
	v_exp_f32_e32 v69, v69
	v_exp_f32_e32 v60, v60
	v_exp_f32_e32 v61, v61
	v_pk_add_f32 v[68:69], v[68:69], 1.0 op_sel_hi:[1,0]
	v_pk_add_f32 v[60:61], v[60:61], 1.0 op_sel_hi:[1,0]
	v_rcp_f32_e32 v68, v68
	v_rcp_f32_e32 v69, v69
	v_rcp_f32_e32 v60, v60
	v_rcp_f32_e32 v61, v61
	v_pk_mul_f32 v[68:69], v[68:69], v[66:67] op_sel:[0,1]
	v_pk_mul_f32 v[60:61], v[60:61], v[66:67] op_sel:[0,1]
	v_pk_mul_f32 v[48:49], v[48:49], v[68:69]
	v_pk_mul_f32 v[50:51], v[50:51], v[60:61]
	v_pk_mul_f32 v[68:69], v[56:57], v[66:67] op_sel_hi:[1,0]
	v_pk_mul_f32 v[56:57], v[56:57], v[52:53]
	v_pk_mul_f32 v[60:61], v[58:59], v[66:67] op_sel_hi:[1,0]
	v_pk_mul_f32 v[58:59], v[58:59], v[54:55]
	v_exp_f32_e32 v68, v68
	v_exp_f32_e32 v69, v69
	v_exp_f32_e32 v60, v60
	v_exp_f32_e32 v61, v61
	v_pk_add_f32 v[68:69], v[68:69], 1.0 op_sel_hi:[1,0]
	v_pk_add_f32 v[60:61], v[60:61], 1.0 op_sel_hi:[1,0]
	v_rcp_f32_e32 v68, v68
	v_rcp_f32_e32 v69, v69
	v_rcp_f32_e32 v60, v60
	v_rcp_f32_e32 v61, v61
	v_pk_mul_f32 v[68:69], v[68:69], v[66:67] op_sel:[0,1]
	v_pk_mul_f32 v[60:61], v[60:61], v[66:67] op_sel:[0,1]
	v_pk_mul_f32 v[52:53], v[56:57], v[68:69]
	v_pk_mul_f32 v[54:55], v[58:59], v[60:61]
	v_cvt_pk_bf16_f32 v48, v48, v49
	v_cvt_pk_bf16_f32 v49, v50, v51
	v_cvt_pk_bf16_f32 v50, v52, v53
	v_mov_b64_e32 v[52:53], s[62:63]
	v_cvt_pk_bf16_f32 v51, v54, v55
	v_mad_i64_i32 v[54:55], s[4:5], v64, s16, v[52:53]
	v_lshl_add_u64 v[54:55], v[54:55], 0, s[38:39]
	v_lshl_add_u64 v[54:55], v[54:55], 0, s[68:69]
	v_lshl_add_u64 v[54:55], v[54:55], 0, v[96:97]
	global_store_dwordx4 v[54:55], v[48:51], off sc1
	s_nop 1
	v_add_u32_e32 v48, 0x90, v130
	v_ashrrev_i32_e32 v49, 31, v48
	v_lshlrev_b64 v[50:51], 6, v[48:49]
	v_lshl_add_u64 v[50:51], v[204:205], 0, v[50:51]
	s_waitcnt vmcnt(7)
	v_add_f32_e32 v49, v156, v157
	v_add_f32_e32 v50, v158, v159
	v_add_f32_e32 v49, v49, v50
	v_mov_b32_e32 v50, v49
	s_nop 1
	v_permlane16_swap_b32_e32 v49, v50
	v_add_f32_e32 v49, v49, v50
	v_mov_b32_e32 v50, v49
	s_nop 1
	v_permlane32_swap_b32_e32 v49, v50
	v_add_f32_e32 v49, v49, v50
	v_fmamk_f32 v49, v49, 0x3a800000, v225
	v_rsq_f32_e32 v50, v49
	s_nop 0
	v_mul_f32_e32 v51, v50, v50
	v_mul_f32_e32 v50, 0xbfb8aa3b, v50
	v_pk_mul_f32 v[54:55], v[44:45], v[50:51] op_sel_hi:[1,0]
	v_pk_mul_f32 v[44:45], v[44:45], v[40:41]
	v_pk_mul_f32 v[40:41], v[46:47], v[50:51] op_sel_hi:[1,0]
	v_pk_mul_f32 v[46:47], v[46:47], v[42:43]
	v_exp_f32_e32 v54, v54
	v_exp_f32_e32 v55, v55
	v_exp_f32_e32 v40, v40
	v_exp_f32_e32 v41, v41
	v_pk_add_f32 v[54:55], v[54:55], 1.0 op_sel_hi:[1,0]
	v_pk_add_f32 v[40:41], v[40:41], 1.0 op_sel_hi:[1,0]
	v_rcp_f32_e32 v54, v54
	v_rcp_f32_e32 v55, v55
	v_rcp_f32_e32 v40, v40
	v_rcp_f32_e32 v41, v41
	v_pk_mul_f32 v[54:55], v[54:55], v[50:51] op_sel:[0,1]
	v_pk_mul_f32 v[40:41], v[40:41], v[50:51] op_sel:[0,1]
	s_nop 0
	v_pk_mul_f32 v[42:43], v[46:47], v[40:41]
	v_pk_mul_f32 v[40:41], v[44:45], v[54:55]
	v_pk_mul_f32 v[54:55], v[36:37], v[50:51] op_sel_hi:[1,0]
	v_pk_mul_f32 v[36:37], v[36:37], v[32:33]
	v_pk_mul_f32 v[44:45], v[38:39], v[50:51] op_sel_hi:[1,0]
	v_pk_mul_f32 v[38:39], v[38:39], v[34:35]
	v_exp_f32_e32 v54, v54
	v_exp_f32_e32 v55, v55
	v_exp_f32_e32 v44, v44
	v_exp_f32_e32 v45, v45
	v_pk_add_f32 v[54:55], v[54:55], 1.0 op_sel_hi:[1,0]
	v_pk_add_f32 v[44:45], v[44:45], 1.0 op_sel_hi:[1,0]
	v_rcp_f32_e32 v54, v54
	v_rcp_f32_e32 v55, v55
	v_rcp_f32_e32 v44, v44
	v_rcp_f32_e32 v45, v45
	v_pk_mul_f32 v[54:55], v[54:55], v[50:51] op_sel:[0,1]
	v_pk_mul_f32 v[44:45], v[44:45], v[50:51] op_sel:[0,1]
	v_pk_mul_f32 v[36:37], v[36:37], v[54:55]
	v_pk_mul_f32 v[38:39], v[38:39], v[44:45]
	v_cvt_pk_bf16_f32 v34, v36, v37
	v_mad_i64_i32 v[36:37], s[4:5], v48, s16, v[52:53]
	v_lshl_add_u64 v[36:37], v[36:37], 0, s[38:39]
	v_lshl_add_u64 v[36:37], v[36:37], 0, s[68:69]
	v_cvt_pk_bf16_f32 v32, v40, v41
	v_cvt_pk_bf16_f32 v33, v42, v43
	v_cvt_pk_bf16_f32 v35, v38, v39
	v_lshl_add_u64 v[36:37], v[36:37], 0, v[96:97]
	global_store_dwordx4 v[36:37], v[32:35], off sc1
	s_nop 1
	v_add_u32_e32 v32, 0xa0, v130
	v_ashrrev_i32_e32 v33, 31, v32
	v_lshlrev_b64 v[34:35], 6, v[32:33]
	v_lshl_add_u64 v[34:35], v[204:205], 0, v[34:35]
	s_waitcnt vmcnt(7)
	v_add_f32_e32 v33, v160, v161
	v_add_f32_e32 v34, v162, v163
	v_add_f32_e32 v33, v33, v34
	v_mov_b32_e32 v34, v33
	s_nop 1
	v_permlane16_swap_b32_e32 v33, v34
	v_add_f32_e32 v33, v33, v34
	v_mov_b32_e32 v34, v33
	s_nop 1
	v_permlane32_swap_b32_e32 v33, v34
	v_add_f32_e32 v33, v33, v34
	v_fmamk_f32 v33, v33, 0x3a800000, v225
	v_rsq_f32_e32 v34, v33
	s_nop 0
	v_mul_f32_e32 v35, v34, v34
	v_mul_f32_e32 v34, 0xbfb8aa3b, v34
	v_pk_mul_f32 v[36:37], v[28:29], v[34:35] op_sel_hi:[1,0]
	v_pk_mul_f32 v[28:29], v[28:29], v[24:25]
	v_pk_mul_f32 v[24:25], v[30:31], v[34:35] op_sel_hi:[1,0]
	v_pk_mul_f32 v[30:31], v[30:31], v[26:27]
	v_exp_f32_e32 v36, v36
	v_exp_f32_e32 v37, v37
	v_exp_f32_e32 v24, v24
	v_exp_f32_e32 v25, v25
	v_pk_add_f32 v[36:37], v[36:37], 1.0 op_sel_hi:[1,0]
	v_pk_add_f32 v[24:25], v[24:25], 1.0 op_sel_hi:[1,0]
	v_rcp_f32_e32 v36, v36
	v_rcp_f32_e32 v37, v37
	v_rcp_f32_e32 v24, v24
	v_rcp_f32_e32 v25, v25
	v_pk_mul_f32 v[36:37], v[36:37], v[34:35] op_sel:[0,1]
	v_pk_mul_f32 v[24:25], v[24:25], v[34:35] op_sel:[0,1]
	s_nop 0
	v_pk_mul_f32 v[26:27], v[30:31], v[24:25]
	v_pk_mul_f32 v[24:25], v[28:29], v[36:37]
	v_pk_mul_f32 v[36:37], v[20:21], v[34:35] op_sel_hi:[1,0]
	v_pk_mul_f32 v[20:21], v[20:21], v[16:17]
	v_pk_mul_f32 v[28:29], v[22:23], v[34:35] op_sel_hi:[1,0]
	v_pk_mul_f32 v[22:23], v[22:23], v[18:19]
	v_exp_f32_e32 v36, v36
	v_exp_f32_e32 v37, v37
	v_exp_f32_e32 v28, v28
	v_exp_f32_e32 v29, v29
	v_pk_add_f32 v[36:37], v[36:37], 1.0 op_sel_hi:[1,0]
	v_pk_add_f32 v[28:29], v[28:29], 1.0 op_sel_hi:[1,0]
	v_rcp_f32_e32 v36, v36
	v_rcp_f32_e32 v37, v37
	v_rcp_f32_e32 v28, v28
	v_rcp_f32_e32 v29, v29
	v_pk_mul_f32 v[36:37], v[36:37], v[34:35] op_sel:[0,1]
	v_pk_mul_f32 v[28:29], v[28:29], v[34:35] op_sel:[0,1]
	v_pk_mul_f32 v[20:21], v[20:21], v[36:37]
	v_pk_mul_f32 v[22:23], v[22:23], v[28:29]
	v_cvt_pk_bf16_f32 v18, v20, v21
	v_mad_i64_i32 v[20:21], s[4:5], v32, s16, v[52:53]
	v_lshl_add_u64 v[20:21], v[20:21], 0, s[38:39]
	v_lshl_add_u64 v[20:21], v[20:21], 0, s[68:69]
	v_cvt_pk_bf16_f32 v16, v24, v25
	v_cvt_pk_bf16_f32 v17, v26, v27
	v_cvt_pk_bf16_f32 v19, v22, v23
	v_lshl_add_u64 v[20:21], v[20:21], 0, v[96:97]
	global_store_dwordx4 v[20:21], v[16:19], off sc1
	s_nop 1
	v_add_u32_e32 v16, 0xb0, v130
	v_ashrrev_i32_e32 v17, 31, v16
	v_lshlrev_b64 v[18:19], 6, v[16:17]
	v_lshl_add_u64 v[18:19], v[204:205], 0, v[18:19]
	s_waitcnt vmcnt(7)
	v_add_f32_e32 v17, v164, v165
	v_add_f32_e32 v18, v166, v167
	v_add_f32_e32 v17, v17, v18
	v_mov_b32_e32 v18, v17
	s_nop 1
	v_permlane16_swap_b32_e32 v17, v18
	v_add_f32_e32 v17, v17, v18
	v_mov_b32_e32 v18, v17
	s_nop 1
	v_permlane32_swap_b32_e32 v17, v18
	v_add_f32_e32 v17, v17, v18
	v_fmamk_f32 v17, v17, 0x3a800000, v225
	v_rsq_f32_e32 v18, v17
	s_nop 0
	v_mul_f32_e32 v19, v18, v18
	v_mul_f32_e32 v18, 0xbfb8aa3b, v18
	v_pk_mul_f32 v[20:21], v[12:13], v[18:19] op_sel_hi:[1,0]
	v_pk_mul_f32 v[12:13], v[12:13], v[8:9]
	v_pk_mul_f32 v[8:9], v[14:15], v[18:19] op_sel_hi:[1,0]
	v_pk_mul_f32 v[14:15], v[14:15], v[10:11]
	v_exp_f32_e32 v20, v20
	v_exp_f32_e32 v21, v21
	v_exp_f32_e32 v8, v8
	v_exp_f32_e32 v9, v9
	v_pk_add_f32 v[20:21], v[20:21], 1.0 op_sel_hi:[1,0]
	v_pk_add_f32 v[8:9], v[8:9], 1.0 op_sel_hi:[1,0]
	v_rcp_f32_e32 v20, v20
	v_rcp_f32_e32 v21, v21
	v_rcp_f32_e32 v8, v8
	v_rcp_f32_e32 v9, v9
	v_pk_mul_f32 v[20:21], v[20:21], v[18:19] op_sel:[0,1]
	v_pk_mul_f32 v[8:9], v[8:9], v[18:19] op_sel:[0,1]
	s_nop 0
	v_pk_mul_f32 v[10:11], v[14:15], v[8:9]
	v_pk_mul_f32 v[8:9], v[12:13], v[20:21]
	v_pk_mul_f32 v[20:21], v[4:5], v[18:19] op_sel_hi:[1,0]
	v_pk_mul_f32 v[4:5], v[4:5], v[0:1]
	v_pk_mul_f32 v[12:13], v[6:7], v[18:19] op_sel_hi:[1,0]
	v_pk_mul_f32 v[6:7], v[6:7], v[2:3]
	v_exp_f32_e32 v20, v20
	v_exp_f32_e32 v21, v21
	v_exp_f32_e32 v12, v12
	v_exp_f32_e32 v13, v13
	v_pk_add_f32 v[20:21], v[20:21], 1.0 op_sel_hi:[1,0]
	v_pk_add_f32 v[12:13], v[12:13], 1.0 op_sel_hi:[1,0]
	v_rcp_f32_e32 v20, v20
	v_rcp_f32_e32 v21, v21
	v_rcp_f32_e32 v12, v12
	v_rcp_f32_e32 v13, v13
	v_pk_mul_f32 v[20:21], v[20:21], v[18:19] op_sel:[0,1]
	v_pk_mul_f32 v[12:13], v[12:13], v[18:19] op_sel:[0,1]
	v_pk_mul_f32 v[4:5], v[4:5], v[20:21]
	v_pk_mul_f32 v[6:7], v[6:7], v[12:13]
	v_cvt_pk_bf16_f32 v2, v4, v5
	v_mad_i64_i32 v[4:5], s[4:5], v16, s16, v[52:53]
	v_lshl_add_u64 v[4:5], v[4:5], 0, s[38:39]
	v_lshl_add_u64 v[4:5], v[4:5], 0, s[68:69]
	v_cvt_pk_bf16_f32 v0, v8, v9
	v_cvt_pk_bf16_f32 v1, v10, v11
	v_cvt_pk_bf16_f32 v3, v6, v7
	v_lshl_add_u64 v[4:5], v[4:5], 0, v[96:97]
	global_store_dwordx4 v[4:5], v[0:3], off sc1
	s_and_b64 vcc, exec, s[36:37]
	s_mov_b64 s[30:31], -1
	s_cbranch_vccnz .LBB0_349

.LBB0_434:
	v_lshlrev_b64 v[98:99], 6, v[132:133]
	v_lshl_add_u64 v[98:99], v[206:207], 0, v[98:99]
	global_load_dwordx4 v[158:161], v[98:99], off
	global_load_dwordx4 v[162:165], v[98:99], off offset:1024
	global_load_dwordx4 v[166:169], v[98:99], off offset:2048
	global_load_dwordx4 v[170:173], v[98:99], off offset:3072
	v_add_u32_e32 v190, 0x80, v132
	v_ashrrev_i32_e32 v191, 31, v190
	v_lshlrev_b64 v[190:191], 6, v[190:191]
	v_lshl_add_u64 v[190:191], v[206:207], 0, v[190:191]
	global_load_dwordx4 v[174:177], v[190:191], off
	global_load_dwordx4 v[178:181], v[190:191], off offset:1024
	global_load_dwordx4 v[182:185], v[190:191], off offset:2048
	global_load_dwordx4 v[186:189], v[190:191], off offset:3072
	s_waitcnt vmcnt(7)
	v_add_f32_e32 v96, v158, v159
	v_add_f32_e32 v98, v160, v161
	v_add_f32_e32 v96, v96, v98
	v_mov_b32_e32 v98, v96
	s_nop 1
	v_permlane16_swap_b32_e32 v96, v98
	v_add_f32_e32 v96, v96, v98
	v_mov_b32_e32 v98, v96
	s_nop 1
	v_permlane32_swap_b32_e32 v96, v98
	v_add_f32_e32 v96, v96, v98
	v_fmamk_f32 v96, v96, 0x3a800000, v225
	v_rsq_f32_e32 v96, v96
	s_nop 0

.LBB0_440:
	v_add_u32_e32 v98, s8, v247
	v_ashrrev_i32_e32 v99, 31, v98
	v_lshl_add_u64 v[134:135], v[98:99], 1, s[30:31]
	v_mad_u64_u32 v[152:153], s[30:31], v132, s93, 0
	v_mov_b32_e32 v96, v153
	v_mad_u64_u32 v[154:155], s[30:31], v133, s93, v[96:97]
	v_mov_b32_e32 v153, v154
	v_lshl_add_u64 v[152:153], v[152:153], 1, v[134:135]
	v_cvt_pk_bf16_f32 v148, v148, v149
	v_cvt_pk_bf16_f32 v149, v150, v151
	v_cvt_pk_bf16_f32 v151, v136, v137
	v_cvt_pk_bf16_f32 v136, v138, v139
	v_cvt_pk_bf16_f32 v137, v142, v143
	v_cvt_pk_bf16_f32 v138, v146, v147
	v_cvt_pk_bf16_f32 v139, v144, v145
	global_store_dwordx4 v[152:153], v[136:139], off offset:256 sc1
	v_cndmask_b32_e64 v96, 0, 1, s[88:89]
	v_cvt_pk_bf16_f32 v150, v140, v141
	v_or_b32_e32 v136, 16, v132
	v_cmp_ne_u32_e64 s[44:45], 1, v96
	s_andn2_b64 vcc, exec, s[88:89]
	v_ashrrev_i32_e32 v137, 31, v136
	global_store_dwordx4 v[152:153], v[148:151], off sc1
	s_cbranch_vccnz .LBB0_442
	v_lshlrev_b64 v[138:139], 6, v[136:137]
	v_lshl_add_u64 v[138:139], v[206:207], 0, v[138:139]
	s_waitcnt vmcnt(7)
	v_add_f32_e32 v96, v162, v163
	v_add_f32_e32 v133, v164, v165
	v_add_f32_e32 v96, v96, v133
	v_mov_b32_e32 v133, v96
	s_nop 1
	v_permlane16_swap_b32_e32 v96, v133
	v_add_f32_e32 v96, v96, v133
	v_mov_b32_e32 v133, v96
	s_nop 1
	v_permlane32_swap_b32_e32 v96, v133
	v_add_f32_e32 v96, v96, v133
	v_fmamk_f32 v96, v96, 0x3a800000, v225
	v_rsq_f32_e32 v96, v96
	s_nop 0
	s_branch .LBB0_443

.LBB0_447:
	v_mad_u64_u32 v[138:139], s[30:31], v136, s93, 0
	v_mov_b32_e32 v96, v139
	v_mad_u64_u32 v[136:137], s[30:31], v137, s93, v[96:97]
	v_mov_b32_e32 v139, v136
	v_cvt_pk_bf16_f32 v120, v120, v121
	v_cvt_pk_bf16_f32 v121, v122, v123
	v_cvt_pk_bf16_f32 v122, v116, v117
	v_or_b32_e32 v116, 32, v132
	v_lshl_add_u64 v[136:137], v[138:139], 1, v[134:135]
	v_cvt_pk_bf16_f32 v128, v128, v129
	v_cvt_pk_bf16_f32 v129, v130, v131
	v_cvt_pk_bf16_f32 v130, v124, v125
	v_cvt_pk_bf16_f32 v131, v126, v127
	v_cvt_pk_bf16_f32 v123, v118, v119
	s_and_b64 vcc, exec, s[44:45]
	v_ashrrev_i32_e32 v117, 31, v116
	global_store_dwordx4 v[136:137], v[128:131], off sc1
	global_store_dwordx4 v[136:137], v[120:123], off offset:256 sc1
	s_cbranch_vccnz .LBB0_449
	v_lshlrev_b64 v[118:119], 6, v[116:117]
	v_lshl_add_u64 v[118:119], v[206:207], 0, v[118:119]
	s_waitcnt vmcnt(7)
	v_add_f32_e32 v96, v166, v167
	v_add_f32_e32 v118, v168, v169
	v_add_f32_e32 v96, v96, v118
	v_mov_b32_e32 v118, v96
	s_nop 1
	v_permlane16_swap_b32_e32 v96, v118
	v_add_f32_e32 v96, v96, v118
	v_mov_b32_e32 v118, v96
	s_nop 1
	v_permlane32_swap_b32_e32 v96, v118
	v_add_f32_e32 v96, v96, v118
	v_fmamk_f32 v96, v96, 0x3a800000, v225
	v_rsq_f32_e32 v96, v96
	s_nop 0
	s_branch .LBB0_450

.LBB0_454:
	v_mad_u64_u32 v[118:119], s[30:31], v116, s93, 0
	v_mov_b32_e32 v96, v119
	v_mad_u64_u32 v[116:117], s[30:31], v117, s93, v[96:97]
	v_mov_b32_e32 v119, v116
	v_cvt_pk_bf16_f32 v104, v104, v105
	v_cvt_pk_bf16_f32 v105, v106, v107
	v_cvt_pk_bf16_f32 v106, v100, v101
	v_or_b32_e32 v100, 48, v132
	v_lshl_add_u64 v[116:117], v[118:119], 1, v[134:135]
	v_cvt_pk_bf16_f32 v112, v112, v113
	v_cvt_pk_bf16_f32 v113, v114, v115
	v_cvt_pk_bf16_f32 v114, v108, v109
	v_cvt_pk_bf16_f32 v115, v110, v111
	v_cvt_pk_bf16_f32 v107, v102, v103
	s_and_b64 vcc, exec, s[44:45]
	v_ashrrev_i32_e32 v101, 31, v100
	global_store_dwordx4 v[116:117], v[112:115], off sc1
	global_store_dwordx4 v[116:117], v[104:107], off offset:256 sc1
	s_cbranch_vccnz .LBB0_456
	v_lshlrev_b64 v[102:103], 6, v[100:101]
	v_lshl_add_u64 v[102:103], v[206:207], 0, v[102:103]
	s_waitcnt vmcnt(7)
	v_add_f32_e32 v96, v170, v171
	v_add_f32_e32 v102, v172, v173
	v_add_f32_e32 v96, v96, v102
	v_mov_b32_e32 v102, v96
	s_nop 1
	v_permlane16_swap_b32_e32 v96, v102
	v_add_f32_e32 v96, v96, v102
	v_mov_b32_e32 v102, v96
	s_nop 1
	v_permlane32_swap_b32_e32 v96, v102
	v_add_f32_e32 v96, v96, v102
	v_fmamk_f32 v96, v96, 0x3a800000, v225
	v_rsq_f32_e32 v96, v96
	s_nop 0
	s_branch .LBB0_457

.LBB0_461:
	v_mad_u64_u32 v[102:103], s[30:31], v100, s93, 0
	v_mov_b32_e32 v96, v103
	v_mad_u64_u32 v[100:101], s[30:31], v101, s93, v[96:97]
	v_mov_b32_e32 v103, v100
	v_cvt_pk_bf16_f32 v84, v84, v85
	v_cvt_pk_bf16_f32 v85, v86, v87
	v_cvt_pk_bf16_f32 v86, v80, v81
	v_add_u32_e32 v80, 0x80, v132
	v_lshl_add_u64 v[100:101], v[102:103], 1, v[134:135]
	v_cvt_pk_bf16_f32 v92, v92, v93
	v_cvt_pk_bf16_f32 v93, v94, v95
	v_cvt_pk_bf16_f32 v94, v88, v89
	v_cvt_pk_bf16_f32 v95, v90, v91
	v_cvt_pk_bf16_f32 v87, v82, v83
	s_and_b64 vcc, exec, s[44:45]
	v_ashrrev_i32_e32 v81, 31, v80
	global_store_dwordx4 v[100:101], v[92:95], off sc1
	global_store_dwordx4 v[100:101], v[84:87], off offset:256 sc1
	s_cbranch_vccnz .LBB0_463
	v_lshlrev_b64 v[82:83], 6, v[80:81]
	v_lshl_add_u64 v[82:83], v[206:207], 0, v[82:83]
	s_waitcnt vmcnt(7)
	v_add_f32_e32 v82, v174, v175
	v_add_f32_e32 v83, v176, v177
	v_add_f32_e32 v82, v82, v83
	v_mov_b32_e32 v83, v82
	s_nop 1
	v_permlane16_swap_b32_e32 v82, v83
	v_add_f32_e32 v82, v82, v83
	v_mov_b32_e32 v83, v82
	s_nop 1
	v_permlane32_swap_b32_e32 v82, v83
	v_add_f32_e32 v82, v82, v83
	v_fmamk_f32 v82, v82, 0x3a800000, v225
	v_rsq_f32_e32 v86, v82
	s_nop 0
	s_branch .LBB0_464

.LBB0_468:
	v_mad_u64_u32 v[72:73], s[30:31], v80, s93, 0
	v_mov_b32_e32 v78, v73
	v_mad_u64_u32 v[78:79], s[30:31], v81, s93, v[78:79]
	v_mov_b32_e32 v73, v78
	v_lshl_add_u64 v[72:73], v[72:73], 1, v[134:135]
	v_cvt_pk_bf16_f32 v81, v64, v65
	v_cvt_pk_bf16_f32 v64, v66, v67
	v_cvt_pk_bf16_f32 v65, v74, v75
	v_cvt_pk_bf16_f32 v66, v68, v69
	v_cvt_pk_bf16_f32 v67, v70, v71
	global_store_dwordx4 v[72:73], v[64:67], off offset:256 sc1
	v_cvt_pk_bf16_f32 v78, v82, v83
	v_cvt_pk_bf16_f32 v79, v84, v85
	v_add_u32_e32 v64, 0x90, v132
	v_cvt_pk_bf16_f32 v80, v76, v77
	s_and_b64 vcc, exec, s[44:45]
	v_ashrrev_i32_e32 v65, 31, v64
	global_store_dwordx4 v[72:73], v[78:81], off sc1
	s_cbranch_vccnz .LBB0_470
	v_lshlrev_b64 v[66:67], 6, v[64:65]
	v_lshl_add_u64 v[66:67], v[206:207], 0, v[66:67]
	s_waitcnt vmcnt(7)
	v_add_f32_e32 v66, v178, v179
	v_add_f32_e32 v67, v180, v181
	v_add_f32_e32 v66, v66, v67
	v_mov_b32_e32 v67, v66
	s_nop 1
	v_permlane16_swap_b32_e32 v66, v67
	v_add_f32_e32 v66, v66, v67
	v_mov_b32_e32 v67, v66
	s_nop 1
	v_permlane32_swap_b32_e32 v66, v67
	v_add_f32_e32 v66, v66, v67
	v_fmamk_f32 v66, v66, 0x3a800000, v225
	v_rsq_f32_e32 v66, v66
	s_nop 0
	s_branch .LBB0_471

.LBB0_475:
	v_mad_u64_u32 v[66:67], s[30:31], v64, s93, 0
	v_mov_b32_e32 v64, v67
	v_mad_u64_u32 v[64:65], s[30:31], v65, s93, v[64:65]
	v_mov_b32_e32 v67, v64
	v_cvt_pk_bf16_f32 v44, v44, v45
	v_cvt_pk_bf16_f32 v45, v46, v47
	v_cvt_pk_bf16_f32 v46, v40, v41
	v_add_u32_e32 v40, 0xa0, v132
	v_lshl_add_u64 v[64:65], v[66:67], 1, v[134:135]
	v_cvt_pk_bf16_f32 v56, v56, v57
	v_cvt_pk_bf16_f32 v57, v58, v59
	v_cvt_pk_bf16_f32 v58, v52, v53
	v_cvt_pk_bf16_f32 v59, v54, v55
	v_cvt_pk_bf16_f32 v47, v42, v43
	s_and_b64 vcc, exec, s[44:45]
	v_ashrrev_i32_e32 v41, 31, v40
	global_store_dwordx4 v[64:65], v[56:59], off sc1
	global_store_dwordx4 v[64:65], v[44:47], off offset:256 sc1
	s_cbranch_vccnz .LBB0_477
	v_lshlrev_b64 v[42:43], 6, v[40:41]
	v_lshl_add_u64 v[42:43], v[206:207], 0, v[42:43]
	s_waitcnt vmcnt(7)
	v_add_f32_e32 v42, v182, v183
	v_add_f32_e32 v43, v184, v185
	v_add_f32_e32 v42, v42, v43
	v_mov_b32_e32 v43, v42
	s_nop 1
	v_permlane16_swap_b32_e32 v42, v43
	v_add_f32_e32 v42, v42, v43
	v_mov_b32_e32 v43, v42
	s_nop 1
	v_permlane32_swap_b32_e32 v42, v43
	v_add_f32_e32 v42, v42, v43
	v_fmamk_f32 v42, v42, 0x3a800000, v225
	v_rsq_f32_e32 v42, v42
	s_nop 0
	s_branch .LBB0_478

.LBB0_482:
	v_mad_u64_u32 v[42:43], s[30:31], v40, s93, 0
	v_mov_b32_e32 v40, v43
	v_mad_u64_u32 v[40:41], s[30:31], v41, s93, v[40:41]
	v_mov_b32_e32 v43, v40
	v_cvt_pk_bf16_f32 v20, v20, v21
	v_cvt_pk_bf16_f32 v21, v22, v23
	v_cvt_pk_bf16_f32 v22, v16, v17
	v_add_u32_e32 v16, 0xb0, v132
	v_lshl_add_u64 v[40:41], v[42:43], 1, v[134:135]
	v_cvt_pk_bf16_f32 v28, v28, v29
	v_cvt_pk_bf16_f32 v29, v30, v31
	v_cvt_pk_bf16_f32 v30, v24, v25
	v_cvt_pk_bf16_f32 v31, v26, v27
	v_cvt_pk_bf16_f32 v23, v18, v19
	s_and_b64 vcc, exec, s[44:45]
	v_ashrrev_i32_e32 v17, 31, v16
	global_store_dwordx4 v[40:41], v[28:31], off sc1
	global_store_dwordx4 v[40:41], v[20:23], off offset:256 sc1
	s_cbranch_vccnz .LBB0_484
	v_lshlrev_b64 v[18:19], 6, v[16:17]
	v_lshl_add_u64 v[18:19], v[206:207], 0, v[18:19]
	s_waitcnt vmcnt(7)
	v_add_f32_e32 v18, v186, v187
	v_add_f32_e32 v19, v188, v189
	v_add_f32_e32 v18, v18, v19
	v_mov_b32_e32 v19, v18
	s_nop 1
	v_permlane16_swap_b32_e32 v18, v19
	v_add_f32_e32 v18, v18, v19
	v_mov_b32_e32 v19, v18
	s_nop 1
	v_permlane32_swap_b32_e32 v18, v19
	v_add_f32_e32 v18, v18, v19
	v_fmamk_f32 v18, v18, 0x3a800000, v225
	v_rsq_f32_e32 v18, v18
	s_nop 0
	s_branch .LBB0_485

.LBB0_542:
	v_lshl_add_u32 v130, s68, 8, v205
	v_ashrrev_i32_e32 v131, 31, v130
	v_lshlrev_b64 v[132:133], 6, v[130:131]
	v_lshl_add_u64 v[132:133], v[206:207], 0, v[132:133]
	global_load_dwordx4 v[146:149], v[132:133], off
	global_load_dwordx4 v[150:153], v[132:133], off offset:1024
	global_load_dwordx4 v[154:157], v[132:133], off offset:2048
	global_load_dwordx4 v[158:161], v[132:133], off offset:3072
	v_add_u32_e32 v178, 0x80, v130
	v_ashrrev_i32_e32 v179, 31, v178
	v_lshlrev_b64 v[178:179], 6, v[178:179]
	v_lshl_add_u64 v[178:179], v[206:207], 0, v[178:179]
	global_load_dwordx4 v[162:165], v[178:179], off
	global_load_dwordx4 v[166:169], v[178:179], off offset:1024
	global_load_dwordx4 v[170:173], v[178:179], off offset:2048
	global_load_dwordx4 v[174:177], v[178:179], off offset:3072
	s_cmp_gt_i32 s77, 7
	s_cselect_b64 s[40:41], -1, 0
	s_lshl_b32 s30, s77, 8
	s_add_i32 s68, s30, 0xfffff800
	s_mov_b64 s[38:39], -1
	s_waitcnt vmcnt(7)
	v_add_f32_e32 v96, v146, v147
	v_add_f32_e32 v132, v148, v149
	v_add_f32_e32 v96, v96, v132
	v_mov_b32_e32 v132, v96
	s_nop 1
	v_permlane16_swap_b32_e32 v96, v132
	v_add_f32_e32 v96, v96, v132
	v_mov_b32_e32 v132, v96
	s_nop 1
	v_permlane32_swap_b32_e32 v96, v132
	v_add_f32_e32 v96, v96, v132
	v_fmamk_f32 v96, v96, 0x3a800000, v225
	v_lshlrev_b64 v[134:135], 11, v[130:131]
	v_rsq_f32_e32 v132, v96
	s_nop 0
	s_and_b64 vcc, exec, s[40:41]
	v_lshlrev_b32_e32 v96, 1, v204
	s_cbranch_vccz .LBB0_544
	v_lshl_add_u64 v[136:137], s[26:27], 0, v[134:135]
	v_lshl_add_u64 v[136:137], s[68:69], 1, v[136:137]
	s_lshl_b32 s30, s62, 1
	s_mov_b32 s31, s69
	v_lshl_add_u64 v[136:137], v[136:137], 0, s[30:31]
	v_lshl_add_u64 v[140:141], v[136:137], 0, v[96:97]
	v_pk_mul_f32 v[138:139], v[128:129], v[132:133] op_sel_hi:[1,0]
	v_pk_mul_f32 v[136:137], v[126:127], v[132:133] op_sel_hi:[1,0]
	v_pk_mul_f32 v[142:143], v[120:121], v[132:133] op_sel_hi:[1,0]
	v_pk_mul_f32 v[144:145], v[118:119], v[132:133] op_sel_hi:[1,0]
	v_cvt_pk_bf16_f32 v136, v136, v137
	v_cvt_pk_bf16_f32 v137, v138, v139
	v_cvt_pk_bf16_f32 v138, v144, v145
	v_cvt_pk_bf16_f32 v139, v142, v143
	global_store_dwordx4 v[140:141], v[136:139], off sc1
	v_pk_mul_f32 v[142:143], v[116:117], v[132:133] op_sel_hi:[1,0]
	v_pk_mul_f32 v[144:145], v[114:115], v[132:133] op_sel_hi:[1,0]
	v_pk_mul_f32 v[138:139], v[124:125], v[132:133] op_sel_hi:[1,0]
	v_pk_mul_f32 v[136:137], v[122:123], v[132:133] op_sel_hi:[1,0]
	s_mov_b64 s[38:39], 0
	v_cvt_pk_bf16_f32 v136, v136, v137
	v_cvt_pk_bf16_f32 v137, v138, v139
	v_cvt_pk_bf16_f32 v138, v144, v145
	v_cvt_pk_bf16_f32 v139, v142, v143
	global_store_dwordx4 v[140:141], v[136:139], off offset:256 sc1

.LBB0_546:
	v_or_b32_e32 v118, 16, v130
	v_ashrrev_i32_e32 v119, 31, v118
	v_lshlrev_b64 v[114:115], 6, v[118:119]
	v_lshl_add_u64 v[114:115], v[206:207], 0, v[114:115]
	s_mov_b64 s[60:61], -1
	s_waitcnt vmcnt(7)
	v_add_f32_e32 v114, v150, v151
	v_add_f32_e32 v115, v152, v153
	v_add_f32_e32 v114, v114, v115
	v_mov_b32_e32 v115, v114
	s_nop 1
	v_permlane16_swap_b32_e32 v114, v115
	v_add_f32_e32 v114, v114, v115
	v_mov_b32_e32 v115, v114
	s_nop 1
	v_permlane32_swap_b32_e32 v114, v115
	v_add_f32_e32 v114, v114, v115
	v_fmamk_f32 v114, v114, 0x3a800000, v225
	v_lshlrev_b64 v[116:117], 11, v[118:119]
	v_rsq_f32_e32 v114, v114
	s_nop 0
	v_cndmask_b32_e64 v115, 0, 1, s[40:41]
	v_cmp_ne_u32_e64 s[38:39], 1, v115
	s_andn2_b64 vcc, exec, s[40:41]
	s_cbranch_vccnz .LBB0_548
	v_lshl_add_u64 v[118:119], s[26:27], 0, v[116:117]
	v_lshl_add_u64 v[118:119], s[68:69], 1, v[118:119]
	s_lshl_b32 s40, s62, 1
	s_mov_b32 s41, s69
	v_lshl_add_u64 v[118:119], v[118:119], 0, s[40:41]
	v_lshl_add_u64 v[122:123], v[118:119], 0, v[96:97]
	v_pk_mul_f32 v[120:121], v[112:113], v[114:115] op_sel_hi:[1,0]
	v_pk_mul_f32 v[118:119], v[110:111], v[114:115] op_sel_hi:[1,0]
	v_pk_mul_f32 v[124:125], v[104:105], v[114:115] op_sel_hi:[1,0]
	v_pk_mul_f32 v[126:127], v[102:103], v[114:115] op_sel_hi:[1,0]
	v_cvt_pk_bf16_f32 v118, v118, v119
	v_cvt_pk_bf16_f32 v119, v120, v121
	v_cvt_pk_bf16_f32 v120, v126, v127
	v_cvt_pk_bf16_f32 v121, v124, v125
	global_store_dwordx4 v[122:123], v[118:121], off sc1
	v_pk_mul_f32 v[124:125], v[100:101], v[114:115] op_sel_hi:[1,0]
	v_pk_mul_f32 v[126:127], v[98:99], v[114:115] op_sel_hi:[1,0]
	v_pk_mul_f32 v[120:121], v[108:109], v[114:115] op_sel_hi:[1,0]
	v_pk_mul_f32 v[118:119], v[106:107], v[114:115] op_sel_hi:[1,0]
	s_mov_b64 s[60:61], 0
	v_cvt_pk_bf16_f32 v118, v118, v119
	v_cvt_pk_bf16_f32 v119, v120, v121
	v_cvt_pk_bf16_f32 v120, v126, v127
	v_cvt_pk_bf16_f32 v121, v124, v125
	global_store_dwordx4 v[122:123], v[118:121], off offset:256 sc1

.LBB0_550:
	v_or_b32_e32 v102, 32, v130
	v_ashrrev_i32_e32 v103, 31, v102
	v_lshlrev_b64 v[98:99], 6, v[102:103]
	v_lshl_add_u64 v[98:99], v[206:207], 0, v[98:99]
	s_mov_b64 s[40:41], -1
	s_waitcnt vmcnt(7)
	v_add_f32_e32 v98, v154, v155
	v_add_f32_e32 v99, v156, v157
	v_add_f32_e32 v98, v98, v99
	v_mov_b32_e32 v99, v98
	s_nop 1
	v_permlane16_swap_b32_e32 v98, v99
	v_add_f32_e32 v98, v98, v99
	v_mov_b32_e32 v99, v98
	s_nop 1
	v_permlane32_swap_b32_e32 v98, v99
	v_add_f32_e32 v98, v98, v99
	v_fmamk_f32 v98, v98, 0x3a800000, v225
	v_rsq_f32_e32 v100, v98
	s_nop 0
	s_and_b64 vcc, exec, s[38:39]
	v_lshlrev_b64 v[98:99], 11, v[102:103]
	s_cbranch_vccnz .LBB0_552
	v_lshl_add_u64 v[102:103], s[26:27], 0, v[98:99]
	v_lshl_add_u64 v[102:103], s[68:69], 1, v[102:103]
	s_lshl_b32 s40, s62, 1
	s_mov_b32 s41, s69
	v_lshl_add_u64 v[102:103], v[102:103], 0, s[40:41]
	v_lshl_add_u64 v[106:107], v[102:103], 0, v[96:97]
	v_pk_mul_f32 v[104:105], v[94:95], v[100:101] op_sel_hi:[1,0]
	v_pk_mul_f32 v[102:103], v[92:93], v[100:101] op_sel_hi:[1,0]
	v_pk_mul_f32 v[108:109], v[86:87], v[100:101] op_sel_hi:[1,0]
	v_pk_mul_f32 v[110:111], v[84:85], v[100:101] op_sel_hi:[1,0]
	v_cvt_pk_bf16_f32 v102, v102, v103
	v_cvt_pk_bf16_f32 v103, v104, v105
	v_cvt_pk_bf16_f32 v104, v110, v111
	v_cvt_pk_bf16_f32 v105, v108, v109
	global_store_dwordx4 v[106:107], v[102:105], off sc1
	v_pk_mul_f32 v[108:109], v[82:83], v[100:101] op_sel_hi:[1,0]
	v_pk_mul_f32 v[110:111], v[80:81], v[100:101] op_sel_hi:[1,0]
	v_pk_mul_f32 v[104:105], v[90:91], v[100:101] op_sel_hi:[1,0]
	v_pk_mul_f32 v[102:103], v[88:89], v[100:101] op_sel_hi:[1,0]
	s_mov_b64 s[40:41], 0
	v_cvt_pk_bf16_f32 v102, v102, v103
	v_cvt_pk_bf16_f32 v103, v104, v105
	v_cvt_pk_bf16_f32 v104, v110, v111
	v_cvt_pk_bf16_f32 v105, v108, v109
	global_store_dwordx4 v[106:107], v[102:105], off offset:256 sc1

.LBB0_554:
	v_or_b32_e32 v84, 48, v130
	v_ashrrev_i32_e32 v85, 31, v84
	v_lshlrev_b64 v[80:81], 6, v[84:85]
	v_lshl_add_u64 v[80:81], v[206:207], 0, v[80:81]
	s_mov_b64 s[40:41], -1
	s_waitcnt vmcnt(7)
	v_add_f32_e32 v80, v158, v159
	v_add_f32_e32 v81, v160, v161
	v_add_f32_e32 v80, v80, v81
	v_mov_b32_e32 v81, v80
	s_nop 1
	v_permlane16_swap_b32_e32 v80, v81
	v_add_f32_e32 v80, v80, v81
	v_mov_b32_e32 v81, v80
	s_nop 1
	v_permlane32_swap_b32_e32 v80, v81
	v_add_f32_e32 v80, v80, v81
	v_fmamk_f32 v80, v80, 0x3a800000, v225
	v_rsq_f32_e32 v82, v80
	s_nop 0
	s_and_b64 vcc, exec, s[38:39]
	v_lshlrev_b64 v[80:81], 11, v[84:85]
	s_cbranch_vccnz .LBB0_556
	v_lshl_add_u64 v[84:85], s[26:27], 0, v[80:81]
	v_lshl_add_u64 v[84:85], s[68:69], 1, v[84:85]
	s_lshl_b32 s40, s62, 1
	s_mov_b32 s41, s69
	v_lshl_add_u64 v[84:85], v[84:85], 0, s[40:41]
	v_lshl_add_u64 v[88:89], v[84:85], 0, v[96:97]
	v_pk_mul_f32 v[86:87], v[78:79], v[82:83] op_sel_hi:[1,0]
	v_pk_mul_f32 v[84:85], v[76:77], v[82:83] op_sel_hi:[1,0]
	v_pk_mul_f32 v[90:91], v[70:71], v[82:83] op_sel_hi:[1,0]
	v_pk_mul_f32 v[92:93], v[68:69], v[82:83] op_sel_hi:[1,0]
	v_cvt_pk_bf16_f32 v84, v84, v85
	v_cvt_pk_bf16_f32 v85, v86, v87
	v_cvt_pk_bf16_f32 v86, v92, v93
	v_cvt_pk_bf16_f32 v87, v90, v91
	global_store_dwordx4 v[88:89], v[84:87], off sc1
	v_pk_mul_f32 v[90:91], v[66:67], v[82:83] op_sel_hi:[1,0]
	v_pk_mul_f32 v[92:93], v[64:65], v[82:83] op_sel_hi:[1,0]
	v_pk_mul_f32 v[86:87], v[74:75], v[82:83] op_sel_hi:[1,0]
	v_pk_mul_f32 v[84:85], v[72:73], v[82:83] op_sel_hi:[1,0]
	s_mov_b64 s[40:41], 0
	v_cvt_pk_bf16_f32 v84, v84, v85
	v_cvt_pk_bf16_f32 v85, v86, v87
	v_cvt_pk_bf16_f32 v86, v92, v93
	v_cvt_pk_bf16_f32 v87, v90, v91
	global_store_dwordx4 v[88:89], v[84:87], off offset:256 sc1

.LBB0_558:
	v_add_u32_e32 v68, 0x80, v130
	v_ashrrev_i32_e32 v69, 31, v68
	v_lshlrev_b64 v[64:65], 6, v[68:69]
	v_lshl_add_u64 v[64:65], v[206:207], 0, v[64:65]
	s_mov_b64 s[40:41], -1
	s_waitcnt vmcnt(7)
	v_add_f32_e32 v64, v162, v163
	v_add_f32_e32 v65, v164, v165
	v_add_f32_e32 v64, v64, v65
	v_mov_b32_e32 v65, v64
	s_nop 1
	v_permlane16_swap_b32_e32 v64, v65
	v_add_f32_e32 v64, v64, v65
	v_mov_b32_e32 v65, v64
	s_nop 1
	v_permlane32_swap_b32_e32 v64, v65
	v_add_f32_e32 v64, v64, v65
	v_fmamk_f32 v64, v64, 0x3a800000, v225
	v_rsq_f32_e32 v66, v64
	s_nop 0
	s_and_b64 vcc, exec, s[38:39]
	v_lshlrev_b64 v[64:65], 11, v[68:69]
	s_cbranch_vccnz .LBB0_560
	v_lshl_add_u64 v[68:69], s[26:27], 0, v[64:65]
	v_lshl_add_u64 v[68:69], s[68:69], 1, v[68:69]
	s_lshl_b32 s40, s62, 1
	s_mov_b32 s41, s69
	v_lshl_add_u64 v[68:69], v[68:69], 0, s[40:41]
	v_lshl_add_u64 v[72:73], v[68:69], 0, v[96:97]
	v_pk_mul_f32 v[70:71], v[50:51], v[66:67] op_sel_hi:[1,0]
	v_pk_mul_f32 v[68:69], v[48:49], v[66:67] op_sel_hi:[1,0]
	v_pk_mul_f32 v[74:75], v[58:59], v[66:67] op_sel_hi:[1,0]
	v_pk_mul_f32 v[76:77], v[56:57], v[66:67] op_sel_hi:[1,0]
	v_cvt_pk_bf16_f32 v68, v68, v69
	v_cvt_pk_bf16_f32 v69, v70, v71
	v_cvt_pk_bf16_f32 v70, v76, v77
	v_cvt_pk_bf16_f32 v71, v74, v75
	global_store_dwordx4 v[72:73], v[68:71], off sc1
	v_pk_mul_f32 v[74:75], v[54:55], v[66:67] op_sel_hi:[1,0]
	v_pk_mul_f32 v[76:77], v[52:53], v[66:67] op_sel_hi:[1,0]
	v_pk_mul_f32 v[70:71], v[62:63], v[66:67] op_sel_hi:[1,0]
	v_pk_mul_f32 v[68:69], v[60:61], v[66:67] op_sel_hi:[1,0]
	s_mov_b64 s[40:41], 0
	v_cvt_pk_bf16_f32 v68, v68, v69
	v_cvt_pk_bf16_f32 v69, v70, v71
	v_cvt_pk_bf16_f32 v70, v76, v77
	v_cvt_pk_bf16_f32 v71, v74, v75
	global_store_dwordx4 v[72:73], v[68:71], off offset:256 sc1

.LBB0_562:
	v_add_u32_e32 v52, 0x90, v130
	v_ashrrev_i32_e32 v53, 31, v52
	v_lshlrev_b64 v[48:49], 6, v[52:53]
	v_lshl_add_u64 v[48:49], v[206:207], 0, v[48:49]
	s_mov_b64 s[40:41], -1
	s_waitcnt vmcnt(7)
	v_add_f32_e32 v48, v166, v167
	v_add_f32_e32 v49, v168, v169
	v_add_f32_e32 v48, v48, v49
	v_mov_b32_e32 v49, v48
	s_nop 1
	v_permlane16_swap_b32_e32 v48, v49
	v_add_f32_e32 v48, v48, v49
	v_mov_b32_e32 v49, v48
	s_nop 1
	v_permlane32_swap_b32_e32 v48, v49
	v_add_f32_e32 v48, v48, v49
	v_fmamk_f32 v48, v48, 0x3a800000, v225
	v_rsq_f32_e32 v50, v48
	s_nop 0
	s_and_b64 vcc, exec, s[38:39]
	v_lshlrev_b64 v[48:49], 11, v[52:53]
	s_cbranch_vccnz .LBB0_564
	v_lshl_add_u64 v[52:53], s[26:27], 0, v[48:49]
	v_lshl_add_u64 v[52:53], s[68:69], 1, v[52:53]
	s_lshl_b32 s40, s62, 1
	s_mov_b32 s41, s69
	v_lshl_add_u64 v[52:53], v[52:53], 0, s[40:41]
	v_lshl_add_u64 v[56:57], v[52:53], 0, v[96:97]
	v_pk_mul_f32 v[54:55], v[46:47], v[50:51] op_sel_hi:[1,0]
	v_pk_mul_f32 v[52:53], v[44:45], v[50:51] op_sel_hi:[1,0]
	v_pk_mul_f32 v[58:59], v[38:39], v[50:51] op_sel_hi:[1,0]
	v_pk_mul_f32 v[60:61], v[36:37], v[50:51] op_sel_hi:[1,0]
	v_cvt_pk_bf16_f32 v52, v52, v53
	v_cvt_pk_bf16_f32 v53, v54, v55
	v_cvt_pk_bf16_f32 v54, v60, v61
	v_cvt_pk_bf16_f32 v55, v58, v59
	global_store_dwordx4 v[56:57], v[52:55], off sc1
	v_pk_mul_f32 v[58:59], v[34:35], v[50:51] op_sel_hi:[1,0]
	v_pk_mul_f32 v[60:61], v[32:33], v[50:51] op_sel_hi:[1,0]
	v_pk_mul_f32 v[54:55], v[42:43], v[50:51] op_sel_hi:[1,0]
	v_pk_mul_f32 v[52:53], v[40:41], v[50:51] op_sel_hi:[1,0]
	s_mov_b64 s[40:41], 0
	v_cvt_pk_bf16_f32 v52, v52, v53
	v_cvt_pk_bf16_f32 v53, v54, v55
	v_cvt_pk_bf16_f32 v54, v60, v61
	v_cvt_pk_bf16_f32 v55, v58, v59
	global_store_dwordx4 v[56:57], v[52:55], off offset:256 sc1

.LBB0_566:
	v_add_u32_e32 v36, 0xa0, v130
	v_ashrrev_i32_e32 v37, 31, v36
	v_lshlrev_b64 v[32:33], 6, v[36:37]
	v_lshl_add_u64 v[32:33], v[206:207], 0, v[32:33]
	s_mov_b64 s[40:41], -1
	s_waitcnt vmcnt(7)
	v_add_f32_e32 v32, v170, v171
	v_add_f32_e32 v33, v172, v173
	v_add_f32_e32 v32, v32, v33
	v_mov_b32_e32 v33, v32
	s_nop 1
	v_permlane16_swap_b32_e32 v32, v33
	v_add_f32_e32 v32, v32, v33
	v_mov_b32_e32 v33, v32
	s_nop 1
	v_permlane32_swap_b32_e32 v32, v33
	v_add_f32_e32 v32, v32, v33
	v_fmamk_f32 v32, v32, 0x3a800000, v225
	v_rsq_f32_e32 v34, v32
	s_nop 0
	s_and_b64 vcc, exec, s[38:39]
	v_lshlrev_b64 v[32:33], 11, v[36:37]
	s_cbranch_vccnz .LBB0_568
	v_lshl_add_u64 v[36:37], s[26:27], 0, v[32:33]
	v_lshl_add_u64 v[36:37], s[68:69], 1, v[36:37]
	s_lshl_b32 s40, s62, 1
	s_mov_b32 s41, s69
	v_lshl_add_u64 v[36:37], v[36:37], 0, s[40:41]
	v_lshl_add_u64 v[40:41], v[36:37], 0, v[96:97]
	v_pk_mul_f32 v[38:39], v[30:31], v[34:35] op_sel_hi:[1,0]
	v_pk_mul_f32 v[36:37], v[28:29], v[34:35] op_sel_hi:[1,0]
	v_pk_mul_f32 v[42:43], v[22:23], v[34:35] op_sel_hi:[1,0]
	v_pk_mul_f32 v[44:45], v[20:21], v[34:35] op_sel_hi:[1,0]
	v_cvt_pk_bf16_f32 v36, v36, v37
	v_cvt_pk_bf16_f32 v37, v38, v39
	v_cvt_pk_bf16_f32 v38, v44, v45
	v_cvt_pk_bf16_f32 v39, v42, v43
	global_store_dwordx4 v[40:41], v[36:39], off sc1
	v_pk_mul_f32 v[42:43], v[18:19], v[34:35] op_sel_hi:[1,0]
	v_pk_mul_f32 v[44:45], v[16:17], v[34:35] op_sel_hi:[1,0]
	v_pk_mul_f32 v[38:39], v[26:27], v[34:35] op_sel_hi:[1,0]
	v_pk_mul_f32 v[36:37], v[24:25], v[34:35] op_sel_hi:[1,0]
	s_mov_b64 s[40:41], 0
	v_cvt_pk_bf16_f32 v36, v36, v37
	v_cvt_pk_bf16_f32 v37, v38, v39
	v_cvt_pk_bf16_f32 v38, v44, v45
	v_cvt_pk_bf16_f32 v39, v42, v43
	global_store_dwordx4 v[40:41], v[36:39], off offset:256 sc1

.LBB0_570:
	v_add_u32_e32 v20, 0xb0, v130
	v_ashrrev_i32_e32 v21, 31, v20
	v_lshlrev_b64 v[16:17], 6, v[20:21]
	v_lshl_add_u64 v[16:17], v[206:207], 0, v[16:17]
	s_mov_b64 s[40:41], -1
	s_waitcnt vmcnt(7)
	v_add_f32_e32 v16, v174, v175
	v_add_f32_e32 v17, v176, v177
	v_add_f32_e32 v16, v16, v17
	v_mov_b32_e32 v17, v16
	s_nop 1
	v_permlane16_swap_b32_e32 v16, v17
	v_add_f32_e32 v16, v16, v17
	v_mov_b32_e32 v17, v16
	s_nop 1
	v_permlane32_swap_b32_e32 v16, v17
	v_add_f32_e32 v16, v16, v17
	v_fmamk_f32 v16, v16, 0x3a800000, v225
	v_rsq_f32_e32 v18, v16
	s_nop 0
	s_and_b64 vcc, exec, s[38:39]
	v_lshlrev_b64 v[16:17], 11, v[20:21]
	s_cbranch_vccz .LBB0_573
	s_andn2_b64 vcc, exec, s[40:41]
	s_cbranch_vccz .LBB0_574
